# fox fast path: QK and PV MFMA runs issued bare (fmamk / bf16 packs moved out of the MFMA gaps)
# baseline (speedup 1.0000x reference)
; DI unsigned pk2(float lo, float hi) { unsigned r; asm volatile("v_cvt_pk_bf16_f32 %0, %1, %2" : "=v"(r) : "v"(lo), "v"(hi)); return r; }
; DI f32x4 mmaT(bf16x8 a_m, bf16x8 b_n, f32x4 c) { return __builtin_amdgcn_mfma_f32_16x16x32_bf16(b_n, a_m, c, 0, 0, 0); }
; template <bool DIAG>
; DI void fox_tile(const bf16_t* sK, const bf16_t* sV, const float* sFk, const bf16x8 (&qf)[2][2], f32x4 (&o)[2][4], float (&mrun)[2], float (&lsum)[2], int key0, int qg0, int fr, int fq, int lane) {
;     ...
; #pragma unroll
;   for (int k2 = 0; k2 < 2; ++k2) {
;     bf16x8 pa[2];
; #pragma unroll
;     for (int mi = 0; mi < 2; ++mi) pa[mi] = mk8(pk2(s[mi][2 * k2][0], s[mi][2 * k2][1]), pk2(s[mi][2 * k2][2], s[mi][2 * k2][3]), pk2(s[mi][2 * k2 + 1][0], s[mi][2 * k2 + 1][1]), pk2(s[mi][2 * k2 + 1][2], s[mi][2 * k2 + 1][3]));
; #pragma unroll
;     for (int d = 0; d < 4; ++d) {
; #pragma unroll
;       for (int mi = 0; mi < 2; ++mi) o[mi][d] = mmaT(pa[mi], vf[k2][d], o[mi][d]);
;     }
;   }
.Lfox1_nm4:
	v_cvt_pk_bf16_f32 v32, v84, v85
	v_cvt_pk_bf16_f32 v33, v86, v87
	v_cvt_pk_bf16_f32 v34, v88, v89
	v_cvt_pk_bf16_f32 v35, v90, v91
	v_cvt_pk_bf16_f32 v24, v92, v93
	v_cvt_pk_bf16_f32 v25, v94, v95
	v_cvt_pk_bf16_f32 v26, v164, v165
	v_cvt_pk_bf16_f32 v27, v166, v167
	s_waitcnt lgkmcnt(8)
	v_mfma_f32_16x16x32_bf16 v[142:145], v[68:71], v[36:39], v[142:145]
	v_mfma_f32_16x16x32_bf16 v[138:141], v[60:63], v[36:39], v[138:141]
	v_mfma_f32_16x16x32_bf16 v[134:137], v[64:67], v[36:39], v[134:137]
	v_mfma_f32_16x16x32_bf16 v[130:133], v[56:59], v[36:39], v[130:133]
	s_waitcnt lgkmcnt(0)
	v_mfma_f32_16x16x32_bf16 v[142:145], v[52:55], v[28:31], v[142:145]
	v_mfma_f32_16x16x32_bf16 v[138:141], v[48:51], v[28:31], v[138:141]
	v_mfma_f32_16x16x32_bf16 v[134:137], v[44:47], v[28:31], v[134:137]
	v_mfma_f32_16x16x32_bf16 v[130:133], v[40:43], v[28:31], v[130:133]
	v_mfma_f32_16x16x32_bf16 v[122:125], v[68:71], v[32:35], v[122:125]
	v_mfma_f32_16x16x32_bf16 v[118:121], v[60:63], v[32:35], v[118:121]
	v_mfma_f32_16x16x32_bf16 v[114:117], v[64:67], v[32:35], v[114:117]
	v_mfma_f32_16x16x32_bf16 v[110:113], v[56:59], v[32:35], v[110:113]
	v_mfma_f32_16x16x32_bf16 v[122:125], v[52:55], v[24:27], v[122:125]
	v_mfma_f32_16x16x32_bf16 v[118:121], v[48:51], v[24:27], v[118:121]
	v_mfma_f32_16x16x32_bf16 v[114:117], v[44:47], v[24:27], v[114:117]
	v_mfma_f32_16x16x32_bf16 v[110:113], v[40:43], v[24:27], v[110:113]
	s_branch .Lfox1_join

; DI float ex2(float x) { return __builtin_amdgcn_exp2f(x); }
; DI f32x4 mmaT(bf16x8 a_m, bf16x8 b_n, f32x4 c) { return __builtin_amdgcn_mfma_f32_16x16x32_bf16(b_n, a_m, c, 0, 0, 0); }
; DI v4i16_t tr_rd(const bf16_t* a) { return __builtin_amdgcn_ds_read_tr16_b64_v4i16((LDSP v4i16_t*)a); }
; DI float shx(float v, int m, int lane) { return __int_as_float(__builtin_amdgcn_ds_bpermute((lane ^ m) << 2, __float_as_int(v))); }
; template <bool DIAG>
; DI void fox_tile(const bf16_t* sK, const bf16_t* sV, const float* sFk, const bf16x8 (&qf)[2][2], f32x4 (&o)[2][4], float (&mrun)[2], float (&lsum)[2], int key0, int qg0, int fr, int fq, int lane) {
;     ...
; #pragma unroll
;   for (int t = 0; t < 4; ++t) {
;     const bf16x8 k0 = *(const bf16x8*)((const unsigned char*)sK + (t * 2) * 1024 + kof), k1 = *(const bf16x8*)((const unsigned char*)sK + (t * 2 + 1) * 1024 + kof);
; #pragma unroll
;     for (int mi = 0; mi < 2; ++mi) { s[mi][t] = mmaT(qf[mi][0], k0, (f32x4){0.f, 0.f, 0.f, 0.f}); s[mi][t] = mmaT(qf[mi][1], k1, s[mi][t]); }
;   }
;   f32x4 fk[4];
; #pragma unroll
;   for (int t = 0; t < 4; ++t) fk[t] = *(const f32x4*)(sFk + 16 * t + 4 * fq);
;   __builtin_amdgcn_sched_barrier(0);
;   bf16x8 vf[2][4];
; #pragma unroll
;   for (int k2 = 0; k2 < 2; ++k2)
; #pragma unroll
;     for (int d = 0; d < 4; ++d) {
;       const bf16_t* a = sV + (32 * k2 + 4 * fq + (fr >> 2)) * 72 + 16 * d + 4 * (fr & 3);
;       const v4i16_t lo = tr_rd(a), hi = tr_rd(a + 16 * 72);
;       vf[k2][d] = __builtin_shufflevector(lo, hi, 0, 1, 2, 3, 4, 5, 6, 7);
;     }
;   __builtin_amdgcn_sched_barrier(0);
; #pragma unroll
;   for (int mi = 0; mi < 2; ++mi) {
;     float mx = -INFINITY;
; #pragma unroll
;     for (int t = 0; t < 4; ++t)
; #pragma unroll
;       for (int j = 0; j < 4; ++j) {
;         float x = __builtin_fmaf(s[mi][t][j], SC2, fk[t][j]);
;         if (DIAG) { if (key0 + 16 * t + 4 * fq + j > qg0 + 16 * mi) x = -INFINITY; }
;         s[mi][t][j] = x; mx = fmaxf(mx, x);
;       }
;     mx = fmaxf(mx, shx(mx, 16, lane)); mx = fmaxf(mx, shx(mx, 32, lane));
;     const float mnew = fmaxf(mrun[mi], mx), alpha = ex2(mrun[mi] - mnew);
;     mrun[mi] = mnew;
;     float ps = 0.f;
; #pragma unroll
;     for (int t = 0; t < 4; ++t)
; #pragma unroll
;       for (int j = 0; j < 4; ++j) { const float pv = ex2(s[mi][t][j] - mnew); s[mi][t][j] = pv; ps += pv; }
;     lsum[mi] = lsum[mi] * alpha + ps;
.LBB0_491:
	s_andn2_b64 vcc, exec, s[4:5]
	s_cbranch_vccnz .LBB0_493
	s_cmp_eq_u32 s98, 0
	s_cbranch_scc1 .Lfox1_slow
	s_waitcnt lgkmcnt(11)
	v_mfma_f32_16x16x32_bf16 v[72:75], v[64:67], v[0:3], v[224:227]
	s_waitcnt lgkmcnt(10)
	v_mfma_f32_16x16x32_bf16 v[72:75], v[68:71], v[4:7], v[72:75]
	s_waitcnt lgkmcnt(9)
	v_mfma_f32_16x16x32_bf16 v[76:79], v[56:59], v[0:3], v[224:227]
	s_waitcnt lgkmcnt(8)
	v_mfma_f32_16x16x32_bf16 v[76:79], v[60:63], v[4:7], v[76:79]
	s_waitcnt lgkmcnt(7)
	v_mfma_f32_16x16x32_bf16 v[80:83], v[48:51], v[0:3], v[224:227]
	s_waitcnt lgkmcnt(6)
	v_mfma_f32_16x16x32_bf16 v[80:83], v[52:55], v[4:7], v[80:83]
	s_waitcnt lgkmcnt(5)
	v_mfma_f32_16x16x32_bf16 v[96:99], v[40:43], v[0:3], v[224:227]
	s_waitcnt lgkmcnt(4)
	v_mfma_f32_16x16x32_bf16 v[96:99], v[44:47], v[4:7], v[96:99]
	s_waitcnt lgkmcnt(0)
	v_mfma_f32_16x16x32_bf16 v[84:87], v[64:67], v[8:11], v[228:231]
	v_mfma_f32_16x16x32_bf16 v[84:87], v[68:71], v[12:15], v[84:87]
	v_mfma_f32_16x16x32_bf16 v[88:91], v[56:59], v[8:11], v[228:231]
	v_mfma_f32_16x16x32_bf16 v[88:91], v[60:63], v[12:15], v[88:91]
	v_mfma_f32_16x16x32_bf16 v[92:95], v[48:51], v[8:11], v[228:231]
	v_mfma_f32_16x16x32_bf16 v[92:95], v[52:55], v[12:15], v[92:95]
	v_mfma_f32_16x16x32_bf16 v[164:167], v[40:43], v[8:11], v[228:231]
	v_mfma_f32_16x16x32_bf16 v[164:167], v[44:47], v[12:15], v[164:167]
	ds_read_b64_tr_b16 v[68:69], v221 offset:9216
	ds_read_b64_tr_b16 v[60:61], v221 offset:9248
	ds_read_b64_tr_b16 v[64:65], v221 offset:9280
	ds_read_b64_tr_b16 v[56:57], v221 offset:9312
	ds_read_b64_tr_b16 v[70:71], v221 offset:11520
	ds_read_b64_tr_b16 v[62:63], v221 offset:11552
	ds_read_b64_tr_b16 v[66:67], v221 offset:11584
	ds_read_b64_tr_b16 v[58:59], v221 offset:11616
	ds_read_b64_tr_b16 v[52:53], v221 offset:13824
	ds_read_b64_tr_b16 v[48:49], v221 offset:13856
	ds_read_b64_tr_b16 v[44:45], v221 offset:13888
	ds_read_b64_tr_b16 v[40:41], v221 offset:13920
	ds_read_b64_tr_b16 v[54:55], v221 offset:16128
	ds_read_b64_tr_b16 v[50:51], v221 offset:16160
	ds_read_b64_tr_b16 v[46:47], v221 offset:16192
	ds_read_b64_tr_b16 v[42:43], v221 offset:16224
	v_fmamk_f32 v72, v72, 0x3e38aa3b, v36
	v_fmamk_f32 v73, v73, 0x3e38aa3b, v37
	v_fmamk_f32 v74, v74, 0x3e38aa3b, v38
	v_fmamk_f32 v75, v75, 0x3e38aa3b, v39
	v_fmamk_f32 v76, v76, 0x3e38aa3b, v32
	v_fmamk_f32 v77, v77, 0x3e38aa3b, v33
	v_fmamk_f32 v78, v78, 0x3e38aa3b, v34
	v_fmamk_f32 v79, v79, 0x3e38aa3b, v35
	v_fmamk_f32 v80, v80, 0x3e38aa3b, v28
	v_fmamk_f32 v81, v81, 0x3e38aa3b, v29
	v_fmamk_f32 v82, v82, 0x3e38aa3b, v30
	v_fmamk_f32 v83, v83, 0x3e38aa3b, v31
	v_fmamk_f32 v96, v96, 0x3e38aa3b, v24
	v_fmamk_f32 v97, v97, 0x3e38aa3b, v25
	v_fmamk_f32 v98, v98, 0x3e38aa3b, v26
	v_fmamk_f32 v99, v99, 0x3e38aa3b, v27
	v_exp_f32_e32 v72, v72
	v_exp_f32_e32 v73, v73
	v_exp_f32_e32 v74, v74
	v_exp_f32_e32 v75, v75
	v_exp_f32_e32 v76, v76
	v_exp_f32_e32 v77, v77
	v_exp_f32_e32 v78, v78
	v_exp_f32_e32 v79, v79
	v_exp_f32_e32 v80, v80
	v_exp_f32_e32 v81, v81
	v_exp_f32_e32 v82, v82
	v_exp_f32_e32 v83, v83
	v_exp_f32_e32 v96, v96
	v_exp_f32_e32 v97, v97
	v_exp_f32_e32 v98, v98
	v_exp_f32_e32 v99, v99
	v_fmamk_f32 v84, v84, 0x3e38aa3b, v36
	v_fmamk_f32 v85, v85, 0x3e38aa3b, v37
	v_fmamk_f32 v86, v86, 0x3e38aa3b, v38
	v_fmamk_f32 v87, v87, 0x3e38aa3b, v39
	v_fmamk_f32 v88, v88, 0x3e38aa3b, v32
	v_fmamk_f32 v89, v89, 0x3e38aa3b, v33
	v_fmamk_f32 v90, v90, 0x3e38aa3b, v34
	v_fmamk_f32 v91, v91, 0x3e38aa3b, v35
	v_fmamk_f32 v92, v92, 0x3e38aa3b, v28
	v_fmamk_f32 v93, v93, 0x3e38aa3b, v29
	v_fmamk_f32 v94, v94, 0x3e38aa3b, v30
	v_fmamk_f32 v95, v95, 0x3e38aa3b, v31
	v_fmamk_f32 v164, v164, 0x3e38aa3b, v24
	v_fmamk_f32 v165, v165, 0x3e38aa3b, v25
	v_fmamk_f32 v166, v166, 0x3e38aa3b, v26
	v_fmamk_f32 v167, v167, 0x3e38aa3b, v27
	v_add_f32_e32 v146, v72, v73
	v_add_f32_e32 v147, v74, v75
	v_add_f32_e32 v148, v76, v77
	v_add_f32_e32 v149, v78, v79
	v_add_f32_e32 v150, v80, v81
	v_add_f32_e32 v151, v82, v83
	v_add_f32_e32 v152, v96, v97
	v_add_f32_e32 v153, v98, v99
	v_add_f32_e32 v146, v146, v147
	v_add_f32_e32 v147, v148, v149
	v_add_f32_e32 v148, v150, v151
	v_add_f32_e32 v149, v152, v153
	v_add_f32_e32 v146, v146, v147
	v_add_f32_e32 v148, v148, v149
	v_add_f32_e32 v146, v146, v148
	v_exp_f32_e32 v84, v84
	v_exp_f32_e32 v85, v85
	v_exp_f32_e32 v86, v86
	v_exp_f32_e32 v87, v87
	v_exp_f32_e32 v88, v88
	v_exp_f32_e32 v89, v89
	v_exp_f32_e32 v90, v90
	v_exp_f32_e32 v91, v91
	v_exp_f32_e32 v92, v92
	v_exp_f32_e32 v93, v93
	v_exp_f32_e32 v94, v94
	v_exp_f32_e32 v95, v95
	v_exp_f32_e32 v164, v164
	v_exp_f32_e32 v165, v165
	v_exp_f32_e32 v166, v166
	v_exp_f32_e32 v167, v167
	v_add_f32_e32 v148, v84, v85
	v_add_f32_e32 v149, v86, v87
	v_add_f32_e32 v150, v88, v89
	v_add_f32_e32 v151, v90, v91
	v_add_f32_e32 v152, v92, v93
	v_add_f32_e32 v153, v94, v95
	v_add_f32_e32 v154, v164, v165
	v_add_f32_e32 v155, v166, v167
	v_add_f32_e32 v148, v148, v149
	v_add_f32_e32 v149, v150, v151
	v_add_f32_e32 v150, v152, v153
	v_add_f32_e32 v151, v154, v155
	v_add_f32_e32 v148, v148, v149
	v_add_f32_e32 v150, v150, v151
	v_add_f32_e32 v148, v148, v150
	v_max_f32_e32 v147, v146, v148
	v_cmp_lt_f32_e32 vcc, 0x69800000, v147
	s_cbranch_vccnz .Lfox1_fallback
	v_add_f32_e32 v128, v128, v146
	v_add_f32_e32 v129, v129, v148
	v_cvt_pk_bf16_f32 v36, v72, v73
	v_cvt_pk_bf16_f32 v37, v74, v75
	v_cvt_pk_bf16_f32 v38, v76, v77
	v_cvt_pk_bf16_f32 v39, v78, v79
	v_cvt_pk_bf16_f32 v28, v80, v81
	v_cvt_pk_bf16_f32 v29, v82, v83
	v_cvt_pk_bf16_f32 v30, v96, v97
	v_cvt_pk_bf16_f32 v31, v98, v99
	s_cmp_eq_u32 s99, 0
	s_cbranch_scc1 .Lfox1_nm2
	s_barrier
